# next-layer K/V cache conversion moved from the norm phase into the MRG1 phase on the 240 WGs without a third unit
# speedup vs baseline: 1.0027x; 1.0027x over previous
; #define LAS __attribute__((address_space(3)))
; DI unsigned xb_add(unsigned* p, unsigned v) { return __hip_atomic_fetch_add(p, v, __ATOMIC_RELAXED, __HIP_MEMORY_SCOPE_AGENT); }
; DI unsigned xb_xcc_id() { return (unsigned)__builtin_amdgcn_s_getreg((3 << 11) | 20) & 0xFu; }
; __global__ void __launch_bounds__(512, 2) mk_fwd(Params p_arg) {
;     extern __shared__ __attribute__((aligned(16))) unsigned char lds[];
;     cg::grid_group grid = cg::this_grid();
;     PP p = (PP)__builtin_amdgcn_kernarg_segment_ptr();
;     const int ph_lo = p_arg.ph_lo, ph_hi = p_arg.ph_hi;
;     LAS unsigned char* ldsl = (LAS unsigned char*)lds;
;     float* ldsf = (float*)lds;
;     volatile LAS unsigned* bst = (volatile LAS unsigned*)(ldsl + 131072);
;     if (threadIdx.x == 0) { bst[0] = 0u; bst[1] = 0u; }
;     __syncthreads();
;     if (threadIdx.x == 0) (void)xb_add((unsigned*)(p->ws + WS_BAR) + XB_XCNT(xb_xcc_id()), 1u);
;     for (int ph = ph_lo; ph < ph_hi; ++ph) {
;         asm volatile("" : "+s"(p));
;         const int l = ph >= 3 ? (ph - 3) / PH_PER_LAYER : 0, s = ph >= 3 ? (ph - 3) % PH_PER_LAYER : -1;
.LBB0_5:
	s_or_b64 exec, exec, s[4:5]
	s_mov_b32 s4, 0
	s_nop 0
	v_writelane_b32 v252, s4, 41
	s_cmp_ge_i32 s14, s15
	s_cbranch_scc1 .LBB0_1031
	v_lshrrev_b32_e32 v1, 20, v0
	v_lshrrev_b32_e32 v0, 10, v0
	s_movk_i32 s70, 0xc000
	v_or_b32_e32 v0, v0, v1
	s_movk_i32 s71, 0x3ff
	s_mov_b32 s19, 0
	s_mov_b32 s18, s3
	v_and_or_b32 v0, v0, s71, v195
	s_lshl_b32 s54, s3, 6
	s_lshl_b32 s57, s3, 3
	s_lshl_b64 s[20:21], s[18:19], 9
	s_lshl_b32 s69, s3, 4
	s_ashr_i32 s67, s3, 31
	v_cmp_eq_u32_e64 s[4:5], 0, v0
	s_lshl_b32 s87, s3, 12
	s_lshl_b64 s[92:93], s[18:19], 13
	s_lshl_b64 s[76:77], s[18:19], 14
	v_writelane_b32 v252, s4, 4
	s_bitcmp1_b32 s3, 0
	v_mov_b32_e32 v1, 0
	v_writelane_b32 v252, s5, 5
	s_cselect_b64 s[4:5], -1, 0
	v_writelane_b32 v252, s4, 6
	s_movk_i32 s63, 0xc00
	v_mov_b32_e32 v210, 0x3a27c5ac
	v_writelane_b32 v252, s5, 7
	s_add_i32 s4, 0, 0xa100
	v_writelane_b32 v252, s4, 8
	s_add_i32 s4, 0, 0x20000
	v_writelane_b32 v252, s4, 9
	s_add_i32 s4, 0, 0x20004
	v_writelane_b32 v252, s4, 10
	v_writelane_b32 v252, s67, 11
	v_writelane_b32 v252, s92, 12
	s_mov_b32 s89, 0x3e0f83e1
	s_movk_i32 s94, 0xffdf
	v_writelane_b32 v252, s93, 13
	v_writelane_b32 v252, s76, 14
	s_mov_b32 s95, 0x8000
	s_movk_i32 s96, 0x7fff
	v_writelane_b32 v252, s77, 15
	v_writelane_b32 v252, s54, 16
	v_writelane_b32 v252, s57, 17
	v_writelane_b32 v252, s69, 18
	v_mov_b32_e32 v211, 0x358637bd
	s_mov_b32 s55, 0x18000
	s_movk_i32 s59, 0x41ff
	s_mov_b32 s56, 0xf149f2ca
	s_mov_b32 s68, 0xbfb8aa3b
	v_mov_b32_e32 v212, 0x1000
	v_mov_b32_e32 v213, 0x2000
	v_mov_b32_e32 v214, 0x29303000
	v_mov_b32_e32 v215, 1
	v_mov_b32_e32 v216, 0x8000
	v_mov_b32_e32 v217, 0xfffffe00
	v_mov_b32_e32 v218, 0xbf
	v_mov_b32_e32 v219, 0x7ff
	v_mov_b32_e32 v242, v1
	v_mov_b32_e32 v243, v1
	v_mov_b32_e32 v244, v1
	v_mov_b32_e32 v245, v1
	s_mov_b64 s[34:35], 0x1000
	s_mov_b64 s[82:83], 0x8000
	s_mov_b64 s[64:65], 0x80
	v_writelane_b32 v252, s87, 19
	v_writelane_b32 v252, s2, 20
	s_branch .LBB0_11

; DI int tidx() { int t = threadIdx.x; asm volatile("" : "+v"(t)); return t; }
; DI int bidx() { int t = blockIdx.x; asm volatile("" : "+s"(t)); return t; }
; DI void st_bf16x8(bf16_t* p, f32x4 a, f32x4 b) { u32x4 o; o[0] = cvtpk(a[0], a[1]); o[1] = cvtpk(a[2], a[3]); o[2] = cvtpk(b[0], b[1]); o[3] = cvtpk(b[2], b[3]); *(u32x4*)p = o; }
; DI void cache_convert(PP p, int l, float* tile) {
;     bf16_t* kc = (bf16_t*)(p->ws + WS_KC);
;     const float* ck = p->in[2] + (size_t)l * 32 * 512 * 512;
;     for (size_t i = (size_t)bidx() * 512 + tidx(); i < (size_t)32 * 512 * 512 / 8; i += (size_t)gridDim.x * 512) {
;         const f32x4 a = *(const f32x4*)(ck + i * 8), b = *(const f32x4*)(ck + i * 8 + 4);
;         st_bf16x8(kc + i * 8, a, b);
; __global__ void __launch_bounds__(512, 2) mk_fwd(Params p_arg) {
;     ...
;             if (l < 3) { phase_norm(p, 1, p->in[10] + (size_t)((l + 1) * 2) * 1024, (const float*)(p->ws + WS_MOD) + (size_t)(l + 1) * 6144, 0, 1024, 11, (const float*)(p->ws + WS_MOD) + (size_t)l * 6144 + 5120); cache_convert(p, l + 1, ldsf); }
.LBB0_187:
	s_or_b64 exec, exec, s[6:7]
	s_cmp_eq_u32 s3, 0x100
	s_cbranch_scc1 .LBB0_196
.Lcc_entry:
	s_mov_b32 s6, s2
	s_ashr_i32 s7, s6, 31
	s_waitcnt vmcnt(0)
	v_mov_b32_e32 v2, v195
	s_lshl_b64 s[6:7], s[6:7], 9
	s_nop 0
	v_ashrrev_i32_e32 v3, 31, v2
	v_lshl_add_u64 v[2:3], s[6:7], 0, v[2:3]
	s_mov_b64 s[6:7], 0x100000
	v_cmp_gt_u64_e32 vcc, s[6:7], v[2:3]
	s_and_saveexec_b64 s[6:7], vcc
	v_readlane_b32 s30, v252, 2
	s_mov_b64 s[28:29], 0xfffff
	v_readlane_b32 s31, v252, 3
	s_cbranch_execz .LBB0_190
	s_load_dwordx2 s[12:13], s[0:1], 0x10
	s_lshl_b32 s18, s27, 23
	s_waitcnt lgkmcnt(0)
	s_add_u32 s8, s10, 0x12900000
	s_addc_u32 s9, s11, 0
	s_lshl_b64 s[16:17], s[18:19], 2
	s_add_u32 s12, s12, s16
	s_addc_u32 s13, s13, s17
	s_mov_b64 s[22:23], 0

; DI CvtJob weight_job(PP p, int j) {
;     bf16_t* W = (bf16_t*)(p->ws + WS_W); bf16_t* wada = (bf16_t*)(p->ws + WS_WADA);
;     const int l = j / 5536; int r = j % 5536;
;     bf16_t* Wl = W + (size_t)l * W_LAYER;
;     if (r < 1344) { const int k0 = (r / 84) * 64, n0 = (r % 84) * 64; const float* src = p->in[11] + (size_t)l * 1024 * 5376;
;         if (n0 < 1024) return mkjob(src, 5376, k0, n0, Wl + O_WIN, 1024, n0, k0);
;         if (n0 < 1536) return mkjob(src, 5376, k0, n0, Wl + O_WV, 1024, n0 - 1024, k0);
;         return mkjob(src, 5376, k0, n0, Wl + O_WIN, 1024, n0 - 512, k0); }
;     r -= 1344;
;     if (r < 128) return mkjob(p->in[24] + (size_t)l * 512 * 1024, 1024, (r / 16) * 64, (r % 16) * 64, Wl + O_WOA, 512, (r % 16) * 64, (r / 16) * 64);
;     r -= 128;
;     if (r < 128) return mkjob(p->in[25] + (size_t)l * 512 * 1024, 1024, (r / 16) * 64, (r % 16) * 64, Wl + O_WOB, 512, (r % 16) * 64, (r / 16) * 64);
;     r -= 128;
;     if (r < 256) return mkjob(p->in[26] + (size_t)l * 1024 * 1024, 1024, (r / 16) * 64, (r % 16) * 64, Wl + O_WO, 1024, (r % 16) * 64, (r / 16) * 64);
;     r -= 256;
;     if (r < 1408) { const int k0 = (r / 88) * 64, n0 = (r % 88) * 64; const int jj = n0 < 2816 ? n0 : n0 - 2816;
;         const int row = (jj >> 7) * 256 + (n0 < 2816 ? 0 : 128) + (jj & 127);
;         return mkjob(p->in[27] + (size_t)l * 1024 * 5632, 5632, k0, n0, Wl + O_WFI, 1024, row, k0); }
;     r -= 1408;
;     if (r < 704) return mkjob(p->in[28] + (size_t)l * 2816 * 1024, 1024, (r / 16) * 64, (r % 16) * 64, Wl + O_WFO, 2816, (r % 16) * 64, (r / 16) * 64);
;     r -= 704;
;     if (r < 8) return mkjob(p->in[15] + (size_t)l * 64 * 512, 512, 0, r * 64, Wl + O_WLR, 256, r * 64, 0);
;     r -= 8;
;     if (r < 8) return mkjob(p->in[17] + (size_t)l * 64 * 512, 512, 0, r * 64, Wl + O_WLR, 256, 512 + r * 64, 64);
;     r -= 8;
;     if (r < 16) return mkjob(p->in[18] + (size_t)l * 128 * 512, 512, (r / 8) * 64, (r % 8) * 64, Wl + O_WLR, 256, 1024 + (r % 8) * 64, 128 + (r / 8) * 64);
;     r -= 16;
;     return mkjob(p->in[8] + (size_t)l * 1024 * 6144, 6144, (r / 96) * 64, (r % 96) * 64, wada, 1024, (size_t)l * 6144 + (r % 96) * 64, (r / 96) * 64);
; DI void cache_convert(PP p, int l, float* tile) {
;     ...
;     cvt_loop(2048, tile, [&](int j) { return cache_job(p, l, j); });
; }
.LBB0_196:
	s_waitcnt lgkmcnt(0)
	v_readlane_b32 s6, v252, 41
	s_nop 3
	s_cmp_eq_u32 s6, 0
	s_cbranch_scc1 .Lcc_ret
	s_mov_b32 s6, 0
	s_nop 0
	v_writelane_b32 v252, s6, 41
	v_readlane_b32 s2, v252, 20
	s_add_i32 s3, s3, 16
.Lcc_ret:
	s_branch .LBB0_323
.LBB0_197:
	s_load_dwordx2 s[6:7], s[0:1], 0xf8
	s_waitcnt vmcnt(0)
	v_mov_b32_e32 v10, v195
	s_mov_b32 s24, s2
	s_cmpk_gt_i32 s24, 0x567f
	s_cbranch_scc1 .LBB0_293
	s_waitcnt lgkmcnt(0)
	s_add_u32 s26, s6, 0x14900000
	s_mul_hi_i32 s8, s24, 0x17ad2209
	s_addc_u32 s27, s7, 0
	s_lshr_b32 s9, s8, 31
	s_ashr_i32 s8, s8, 9
	s_add_i32 s12, s8, s9
	s_mul_i32 s8, s12, 0x15a0
	s_sub_i32 s33, s24, s8
	s_ashr_i32 s13, s12, 31
	s_mul_i32 s9, s12, 0x1fc0000
	s_mul_hi_i32 s8, s12, 0x1fc0000
	s_add_u32 s30, s6, s9
	s_addc_u32 s31, s7, s8
	s_cmpk_gt_i32 s33, 0x53f
	s_mov_b64 s[16:17], -1
	s_cbranch_scc0 .LBB0_233
	s_cmpk_gt_u32 s33, 0x5bf
	s_cbranch_scc0 .LBB0_230
	s_cmpk_gt_u32 s33, 0x63f
	s_cbranch_scc0 .LBB0_227
	s_cmpk_gt_u32 s33, 0x73f
	s_cbranch_scc0 .LBB0_224
	s_cmpk_gt_u32 s33, 0xcbf
	s_cbranch_scc0 .LBB0_221
	s_cmpk_gt_u32 s33, 0xf7f
	s_cbranch_scc0 .LBB0_218
	s_cmpk_gt_u32 s33, 0xf87
	s_cbranch_scc0 .LBB0_215
	s_cmpk_gt_u32 s33, 0xf8f
	s_cbranch_scc0 .LBB0_212
	s_cmpk_gt_u32 s33, 0xf9f
	s_mov_b64 s[10:11], -1
	s_cbranch_scc0 .LBB0_208
	s_load_dwordx2 s[8:9], s[0:1], 0x40
	s_mul_i32 s11, s12, 0x1800000
	s_mul_hi_i32 s10, s12, 0x1800000
	s_mul_i32 s18, s12, 0x1800
	s_waitcnt lgkmcnt(0)
	s_add_u32 s11, s8, s11
	s_addc_u32 s10, s9, s10
	s_add_i32 s8, s33, 0xf060
	s_and_b32 s9, s8, 0xffff
	s_mul_i32 s9, s9, 0xaaab
	s_lshr_b32 s16, s9, 16
	s_lshr_b32 s9, s9, 22
	s_mulk_i32 s9, 0x60
	s_sub_i32 s17, s8, s9
	s_lshl_b32 s8, s17, 6
	s_and_b32 s8, s8, 0xffc0
	s_mul_hi_i32 s9, s12, 0x1800
	s_add_u32 s8, s18, s8
	s_addc_u32 s9, s9, 0
	s_and_b32 s16, s16, 0xffc0
	s_mul_i32 s18, s16, 0x6000
	s_add_u32 s11, s11, s18
	s_addc_u32 s10, s10, 0
	s_lshl_b32 s17, s17, 8
	s_and_b32 s17, s17, 0x3ff00
	s_add_u32 s22, s11, s17
	s_addc_u32 s23, s10, 0
	s_lshl_b64 s[8:9], s[8:9], 11
	s_add_u32 s8, s26, s8
	s_addc_u32 s9, s27, s9
	s_lshl_b32 s10, s16, 1
	s_add_u32 s8, s8, s10
	s_addc_u32 s9, s9, 0
	s_mov_b64 s[10:11], 0

; #define LAS __attribute__((address_space(3)))
; DI unsigned xb_add(unsigned* p, unsigned v) { return __hip_atomic_fetch_add(p, v, __ATOMIC_RELAXED, __HIP_MEMORY_SCOPE_AGENT); }
; DI unsigned xb_xcc_id() { return (unsigned)__builtin_amdgcn_s_getreg((3 << 11) | 20) & 0xFu; }
; DI void xcd_barrier(unsigned* bar, volatile LAS unsigned* st) {
;     asm volatile("s_waitcnt vmcnt(0)" ::: "memory");
;     __syncthreads();
;     if (threadIdx.x == 0) {
;         const unsigned x = xb_xcc_id();
;         __builtin_amdgcn_s_waitcnt(0);
;         unsigned nloc = st[0], nx = st[1];
;         if (nloc == 0u) { xcd_barrier_complete(bar, x, nloc, nx); st[0] = nloc; st[1] = nx; }
;         const unsigned old = xb_add(&bar[XB_XSUB(x)], 1u);
; __global__ void __launch_bounds__(512, 2) mk_fwd(Params p_arg) {
;     ...
;         else if (s == 0) epi = EPI_IN; else if (s == 2) epi = EPI_LR; else if (s == 4) epi = EPI_MRG0; else if (s == 5) epi = EPI_MRG1;
;     ...
;             if (l < 3) { phase_norm(p, 1, p->in[10] + (size_t)((l + 1) * 2) * 1024, (const float*)(p->ws + WS_MOD) + (size_t)(l + 1) * 6144, 0, 1024, 11, (const float*)(p->ws + WS_MOD) + (size_t)l * 6144 + 5120); cache_convert(p, l + 1, ldsf); }
.LBB0_965:
	v_readlane_b32 s2, v252, 20
	v_readlane_b32 s54, v252, 16
	v_readlane_b32 s57, v252, 17
	v_readlane_b32 s69, v252, 18
	s_barrier
	s_cmp_eq_u32 s25, 4
	s_cbranch_scc0 .Lcc_no
	s_cmp_eq_u32 s3, 0x100
	s_cbranch_scc0 .Lcc_no
	s_cmp_lt_i32 s14, 36
	s_cbranch_scc0 .Lcc_no
	s_cmp_lt_u32 s2, 16
	s_cbranch_scc1 .Lcc_no
	s_add_i32 s4, s14, -3
	s_mul_hi_u32 s5, s4, 0xba2e8ba3
	s_lshr_b32 s27, s5, 3
	s_add_i32 s27, s27, 1
	s_load_dwordx2 s[10:11], s[0:1], 0xf8
	s_sub_i32 s2, s2, 16
	s_sub_i32 s3, s3, 16
	s_mov_b32 s4, 1
	s_nop 0
	v_writelane_b32 v252, s4, 41
	s_waitcnt lgkmcnt(0)
	s_branch .Lcc_entry
.Lcc_no:
.LBB0_966:
	s_add_i32 s18, s14, 1
	s_cmp_ge_i32 s18, s15
	s_mov_b64 s[4:5], -1
	s_cbranch_scc1 .LBB0_10
	s_waitcnt vmcnt(0)
	s_waitcnt vmcnt(0) lgkmcnt(0)
	s_barrier
	s_mov_b64 s[4:5], exec
	v_readlane_b32 s6, v252, 0
	v_readlane_b32 s7, v252, 1
	s_and_b64 s[6:7], s[4:5], s[6:7]
	s_mov_b64 exec, s[6:7]
	s_cbranch_execz .LBB0_1020
	v_readlane_b32 s9, v252, 9
	s_load_dwordx2 s[6:7], s[0:1], 0xf8
	s_getreg_b32 s8, hwreg(HW_REG_XCC_ID, 0, 4)
	v_mov_b32_e32 v0, s9
	s_waitcnt vmcnt(0) expcnt(0) lgkmcnt(0)
	ds_read_b32 v3, v0
	v_readlane_b32 s9, v252, 10
	s_and_b32 s14, s8, 15
	s_waitcnt lgkmcnt(0)
	v_cmp_ne_u32_e32 vcc, 0, v3
	v_mov_b32_e32 v0, s9
	ds_read_b32 v2, v0
	s_cbranch_vccnz .LBB0_984
	s_add_u32 s8, s6, 0x29300200
	s_addc_u32 s9, s7, 0
	s_add_u32 s10, s6, 0x29300400
	s_addc_u32 s11, s7, 0
	s_add_u32 s12, s6, 0x29300500
	s_addc_u32 s13, s7, 0
	s_add_u32 s22, s6, 0x29300600
	s_addc_u32 s23, s7, 0
	s_add_u32 s28, s6, 0x29300700
	s_addc_u32 s29, s7, 0
	s_add_u32 s30, s6, 0x29300800
	s_addc_u32 s31, s7, 0
	s_add_u32 s36, s6, 0x29300900
	s_addc_u32 s37, s7, 0
	s_add_u32 s38, s6, 0x29300a00
	s_addc_u32 s39, s7, 0
	s_add_u32 s40, s6, 0x29300b00
	s_addc_u32 s41, s7, 0
	s_add_u32 s50, s6, 0x29300c00
	s_addc_u32 s51, s7, 0
	s_add_u32 s52, s6, 0x29300d00
	s_addc_u32 s53, s7, 0
	s_add_u32 s60, s6, 0x29300e00
	s_addc_u32 s61, s7, 0
	s_add_u32 s62, s6, 0x29300f00
	s_addc_u32 s63, s7, 0
	s_add_u32 s66, s6, 0x29301000
	s_addc_u32 s67, s7, 0
	s_add_u32 s70, s6, 0x29301100
	s_addc_u32 s71, s7, 0
	s_add_u32 s72, s6, 0x29301200
	s_addc_u32 s73, s7, 0
	s_add_u32 s74, s6, 0x29301300
	s_addc_u32 s75, s7, 0
	s_mov_b32 s24, 1
	s_branch .LBB0_972
